# added streamlined steady-state attention loops (fewer scalar/control instructions per KV tile) on top of v046
# speedup vs baseline: 1.0141x; 1.0141x over previous
; #define ATT_EVEN(j_, k2_, v1_) do { if (!F32) { if ((j_) + 2 < nt) ATT_DMAK((j_) + 2, k2_); if ((j_) + 1 < nt) ATT_DMAV((j_) + 1, v1_); } } while (0)
; template <bool F32>
; __device__ __forceinline__ void attn_unit(const AUnit& U, LAS unsigned char* lds, float lam, const float* subg) {
;     ...
; #pragma unroll 1
;         for (int it = 0; it <= nt; ++it) {
;             ATT_EVEN(it, r0, r2);
;             if (it >= 1 && it <= mnt) ATT_SM(it - 1);
;             ATT_MM((it >= 1 && it <= mnt), (it < mnt), r0, r1);
.LBB0_704:
	s_min_i32 s30, s85, s87
	s_cmp_lt_i32 s95, 1
	s_cbranch_scc1 .Lc1_gen
	s_cmp_ge_i32 s95, s30
	s_cbranch_scc1 .Lc1_gen
	s_andn2_b64 vcc, exec, s[4:5]
	s_cbranch_vccz .Lc1_steady

; #define ATT_BASEPRIO_EARLY() do { if (comp) __builtin_amdgcn_s_setprio(1); } while (0)
; template <bool F32>
; __device__ __forceinline__ void attn_unit(const AUnit& U, LAS unsigned char* lds, float lam, const float* subg) {
;     ...
;     const int mnt = active ? my_nt : 0;
;     ATT_BASEPRIO_EARLY();
;     bf16x8 pa[4];
; #pragma unroll
;     for (int k = 0; k < 4; ++k) pa[k] = (bf16x8){0, 0, 0, 0, 0, 0, 0, 0};
;     f32x16 p0, p1;
.Lc1_steady:
	s_add_i32 m0, s8, s24
	v_lshl_add_u64 v[4:5], s[22:23], 0, v[146:147]
	v_lshl_add_u64 v[2:3], s[22:23], 0, v[148:149]
	global_load_lds_dwordx4 v[4:5], off
	s_addk_i32 m0, 0x400
	s_add_u32 s28, s22, 0x1fe0000
	global_load_lds_dwordx4 v[2:3], off
	s_addc_u32 s29, s23, 0
	v_lshl_add_u64 v[2:3], s[28:29], 0, v[152:153]
	v_lshl_add_u64 v[4:5], s[28:29], 0, v[150:151]
	s_add_i32 m0, s92, s94
	s_nop 0
	global_load_lds_dwordx4 v[4:5], off
	s_addk_i32 m0, 0x400
	s_nop 0
	global_load_lds_dwordx4 v[2:3], off
	v_exp_f32_e32 v80, v80
	v_exp_f32_e32 v81, v81
	v_exp_f32_e32 v82, v82
	v_exp_f32_e32 v83, v83
	v_exp_f32_e32 v84, v84
	v_exp_f32_e32 v85, v85
	v_exp_f32_e32 v86, v86
	v_exp_f32_e32 v87, v87
	v_add_f32_e32 v2, v80, v84
	v_add_f32_e32 v3, v81, v85
	v_add_f32_e32 v4, v82, v86
	v_add_f32_e32 v5, v83, v87
	v_cvt_pk_bf16_f32 v128, v80, v81
	v_cvt_pk_bf16_f32 v129, v82, v83
	v_exp_f32_e32 v88, v88
	v_exp_f32_e32 v89, v89
	v_exp_f32_e32 v90, v90
	v_exp_f32_e32 v91, v91
	v_cvt_pk_bf16_f32 v130, v84, v85
	v_cvt_pk_bf16_f32 v131, v86, v87
	v_add_f32_e32 v2, v2, v88
	v_add_f32_e32 v3, v3, v89
	v_add_f32_e32 v4, v4, v90
	v_add_f32_e32 v5, v5, v91
	v_exp_f32_e32 v92, v92
	v_exp_f32_e32 v93, v93
	v_exp_f32_e32 v94, v94
	v_exp_f32_e32 v95, v95
	v_cvt_pk_bf16_f32 v132, v88, v89
	v_cvt_pk_bf16_f32 v133, v90, v91
	v_add_f32_e32 v2, v2, v92
	v_add_f32_e32 v3, v3, v93
	v_add_f32_e32 v4, v4, v94
	v_add_f32_e32 v5, v5, v95
	v_exp_f32_e32 v96, v96
	v_exp_f32_e32 v97, v97
	v_exp_f32_e32 v98, v98
	v_exp_f32_e32 v99, v99
	v_cvt_pk_bf16_f32 v134, v92, v93
	v_cvt_pk_bf16_f32 v135, v94, v95
	v_add_f32_e32 v2, v2, v96
	v_add_f32_e32 v3, v3, v97
	v_add_f32_e32 v4, v4, v98
	v_add_f32_e32 v5, v5, v99
	v_exp_f32_e32 v100, v100
	v_exp_f32_e32 v101, v101
	v_exp_f32_e32 v102, v102
	v_exp_f32_e32 v103, v103
	v_cvt_pk_bf16_f32 v136, v96, v97
	v_cvt_pk_bf16_f32 v137, v98, v99
	v_add_f32_e32 v2, v2, v100
	v_add_f32_e32 v3, v3, v101
	v_add_f32_e32 v4, v4, v102
	v_add_f32_e32 v5, v5, v103
	v_exp_f32_e32 v104, v104
	v_exp_f32_e32 v105, v105
	v_exp_f32_e32 v106, v106
	v_exp_f32_e32 v107, v107
	v_cvt_pk_bf16_f32 v138, v100, v101
	v_cvt_pk_bf16_f32 v139, v102, v103
	v_add_f32_e32 v2, v2, v104
	v_add_f32_e32 v3, v3, v105
	v_add_f32_e32 v4, v4, v106
	v_add_f32_e32 v5, v5, v107
	v_exp_f32_e32 v108, v108
	v_exp_f32_e32 v109, v109
	v_exp_f32_e32 v110, v110
	v_exp_f32_e32 v111, v111
	v_cvt_pk_bf16_f32 v140, v104, v105
	v_cvt_pk_bf16_f32 v141, v106, v107
	v_add_f32_e32 v2, v2, v108
	v_add_f32_e32 v3, v3, v109
	v_add_f32_e32 v4, v4, v110
	v_add_f32_e32 v5, v5, v111
	v_add_f32_e32 v2, v2, v3
	v_add_f32_e32 v4, v4, v5
	v_cvt_pk_bf16_f32 v142, v108, v109
	v_add_f32_e32 v2, v2, v4
	v_cvt_pk_bf16_f32 v143, v110, v111
	v_add_f32_e32 v165, v165, v2
	v_add_u32_e32 v0, s24, v191
	v_add_u32_e32 v14, s24, v192
	v_add_u32_e32 v15, s24, v193
	v_add_u32_e32 v171, s24, v194
	v_add_u32_e32 v180, s24, v195
	v_add_u32_e32 v181, s24, v196
	v_add_u32_e32 v253, s24, v197
	v_add_u32_e32 v254, s24, v187
	v_add_u32_e32 v249, s93, v145
	v_add_u32_e32 v250, s93, v159
	v_add_u32_e32 v251, s93, v160
	v_add_u32_e32 v252, s93, v161
	ds_read_b64_tr_b16 v[2:3], v0 offset:49152
	ds_read_b64_tr_b16 v[4:5], v14 offset:49152
	ds_read_b64_tr_b16 v[6:7], v15 offset:49152
	ds_read_b64_tr_b16 v[8:9], v171 offset:49152
	ds_read_b64_tr_b16 v[10:11], v180 offset:49152
	ds_read_b64_tr_b16 v[12:13], v181 offset:49152
	ds_read_b64_tr_b16 v[172:173], v253 offset:49152
	ds_read_b64_tr_b16 v[174:175], v254 offset:49152
	ds_read_b64_tr_b16 v[198:199], v0 offset:53248
	ds_read_b64_tr_b16 v[200:201], v14 offset:53248
	ds_read_b64_tr_b16 v[202:203], v15 offset:53248
	ds_read_b64_tr_b16 v[204:205], v171 offset:53248
	ds_read_b64_tr_b16 v[206:207], v180 offset:53248
	ds_read_b64_tr_b16 v[208:209], v181 offset:53248
	s_setprio 2
	s_waitcnt lgkmcnt(12)
; #define ATT_BAR() do { asm volatile("s_waitcnt lgkmcnt(0)" ::: "memory"); __builtin_amdgcn_s_barrier(); asm volatile("" ::: "memory"); } while (0)
; #define ATT_EVEN(j_, k2_, v1_) do { if (!F32) { if ((j_) + 2 < nt) ATT_DMAK((j_) + 2, k2_); if ((j_) + 1 < nt) ATT_DMAV((j_) + 1, v1_); } } while (0)
; template <bool F32>
; __device__ __forceinline__ void attn_unit(const AUnit& U, LAS unsigned char* lds, float lam, const float* subg) {
;     ...
;         for (int it = 0; it <= nt; ++it) {
;             ATT_EVEN(it, r0, r2);
;             if (it >= 1 && it <= mnt) ATT_SM(it - 1);
;             ATT_MM((it >= 1 && it <= mnt), (it < mnt), r0, r1);
;             ATT_ODD(it, r2, r1);
;             ATT_BAR();
;             { const int t_ = r0; r0 = r1; r1 = r2; r2 = t_; }
	v_mfma_f32_32x32x16_bf16 v[64:79], v[2:5], v[128:131], v[64:79]
	ds_read_b64_tr_b16 v[176:177], v253 offset:53248
	ds_read_b64_tr_b16 v[178:179], v254 offset:53248
	s_waitcnt lgkmcnt(12)
	v_mfma_f32_32x32x16_bf16 v[48:63], v[6:9], v[128:131], v[48:63]
	ds_read_b64_tr_b16 v[2:3], v0 offset:57344
	ds_read_b64_tr_b16 v[4:5], v14 offset:57344
	s_waitcnt lgkmcnt(12)
	v_mfma_f32_32x32x16_bf16 v[32:47], v[10:13], v[128:131], v[32:47]
	ds_read_b64_tr_b16 v[6:7], v15 offset:57344
	ds_read_b64_tr_b16 v[8:9], v171 offset:57344
	s_waitcnt lgkmcnt(12)
	v_mfma_f32_32x32x16_bf16 v[16:31], v[172:175], v[128:131], v[16:31]
	ds_read_b64_tr_b16 v[10:11], v180 offset:57344
	ds_read_b64_tr_b16 v[12:13], v181 offset:57344
	s_waitcnt lgkmcnt(12)
	v_mfma_f32_32x32x16_bf16 v[64:79], v[198:201], v[132:135], v[64:79]
	ds_read_b64_tr_b16 v[172:173], v253 offset:57344
	ds_read_b64_tr_b16 v[174:175], v254 offset:57344
	s_waitcnt lgkmcnt(12)
	v_mfma_f32_32x32x16_bf16 v[48:63], v[202:205], v[132:135], v[48:63]
	ds_read_b64_tr_b16 v[198:199], v0 offset:61440
	ds_read_b64_tr_b16 v[200:201], v14 offset:61440
	s_waitcnt lgkmcnt(12)
	v_mfma_f32_32x32x16_bf16 v[32:47], v[206:209], v[132:135], v[32:47]
	ds_read_b64_tr_b16 v[202:203], v15 offset:61440
	ds_read_b64_tr_b16 v[204:205], v171 offset:61440
	s_waitcnt lgkmcnt(12)
	v_mfma_f32_32x32x16_bf16 v[16:31], v[176:179], v[132:135], v[16:31]
	ds_read_b64_tr_b16 v[206:207], v180 offset:61440
	ds_read_b64_tr_b16 v[208:209], v181 offset:61440
	s_waitcnt lgkmcnt(12)
	v_mfma_f32_32x32x16_bf16 v[64:79], v[2:5], v[136:139], v[64:79]
	ds_read_b64_tr_b16 v[176:177], v253 offset:61440
	ds_read_b64_tr_b16 v[178:179], v254 offset:61440
	s_waitcnt lgkmcnt(12)
	v_mfma_f32_32x32x16_bf16 v[48:63], v[6:9], v[136:139], v[48:63]
	ds_read_b128 v[2:5], v249
	s_waitcnt lgkmcnt(11)
	v_mfma_f32_32x32x16_bf16 v[32:47], v[10:13], v[136:139], v[32:47]
	ds_read_b128 v[6:9], v249 offset:8192
	s_waitcnt lgkmcnt(10)
	v_mfma_f32_32x32x16_bf16 v[16:31], v[172:175], v[136:139], v[16:31]
	ds_read_b128 v[10:13], v250
	s_waitcnt lgkmcnt(9)
	v_mfma_f32_32x32x16_bf16 v[64:79], v[198:201], v[140:143], v[64:79]
	ds_read_b128 v[172:175], v250 offset:8192
	s_waitcnt lgkmcnt(8)
	v_mfma_f32_32x32x16_bf16 v[48:63], v[202:205], v[140:143], v[48:63]
	ds_read_b128 v[198:201], v251
	s_waitcnt lgkmcnt(7)
	v_mfma_f32_32x32x16_bf16 v[32:47], v[206:209], v[140:143], v[32:47]
	ds_read_b128 v[202:205], v251 offset:8192
	s_waitcnt lgkmcnt(6)
	v_mfma_f32_32x32x16_bf16 v[16:31], v[176:179], v[140:143], v[16:31]
	ds_read_b128 v[206:209], v252
	ds_read_b128 v[176:179], v252 offset:8192
	s_waitcnt lgkmcnt(7)
	v_mfma_f32_32x32x16_bf16 v[80:95], v[2:5], v[112:115], 0
	s_waitcnt lgkmcnt(6)
	v_mfma_f32_32x32x16_bf16 v[96:111], v[6:9], v[112:115], 0
	s_waitcnt lgkmcnt(5)
	v_mfma_f32_32x32x16_bf16 v[80:95], v[10:13], v[116:119], v[80:95]
	s_waitcnt lgkmcnt(4)
	v_mfma_f32_32x32x16_bf16 v[96:111], v[172:175], v[116:119], v[96:111]
	s_waitcnt lgkmcnt(3)
	v_mfma_f32_32x32x16_bf16 v[80:95], v[198:201], v[120:123], v[80:95]
	s_waitcnt lgkmcnt(2)
	v_mfma_f32_32x32x16_bf16 v[96:111], v[202:205], v[120:123], v[96:111]
	s_waitcnt lgkmcnt(1)
	v_mfma_f32_32x32x16_bf16 v[80:95], v[206:209], v[124:127], v[80:95]
	s_waitcnt lgkmcnt(0)
	v_mfma_f32_32x32x16_bf16 v[96:111], v[176:179], v[124:127], v[96:111]
	s_setprio 1
	s_waitcnt vmcnt(4)
	s_waitcnt lgkmcnt(0)
	s_barrier
	s_add_u32 s22, s22, 0x20000
	s_addc_u32 s23, s23, 0
	s_mov_b32 s96, s24
	s_mov_b32 s24, s93
	s_mov_b32 s93, s94
	s_mov_b32 s94, s96
	s_add_i32 s95, s95, 1
	s_cmp_lt_i32 s95, s30
	s_cbranch_scc1 .Lc1_steady
	s_branch .LBB0_704

; #define ATT_EVEN(j_, k2_, v1_) do { if (!F32) { if ((j_) + 2 < nt) ATT_DMAK((j_) + 2, k2_); if ((j_) + 1 < nt) ATT_DMAV((j_) + 1, v1_); } } while (0)
; template <bool F32>
; __device__ __forceinline__ void attn_unit(const AUnit& U, LAS unsigned char* lds, float lam, const float* subg) {
;     ...
; #pragma unroll 1
;         for (int it = 0; it <= nt; ++it) {
;             ATT_EVEN(it, r0, r2);
;             ATT_MM((it >= 1 && it <= mnt), (it < mnt), r0, r1);
.LBB0_735:
	s_min_i32 s94, s85, s87
	s_cmp_lt_i32 s31, 1
	s_cbranch_scc1 .Lc0_gen
	s_cmp_ge_i32 s31, s94
	s_cbranch_scc1 .Lc0_gen
	s_andn2_b64 vcc, exec, s[4:5]
	s_cbranch_vccz .Lc0_steady

; #define ATT_BASEPRIO_EARLY() do { if (comp) __builtin_amdgcn_s_setprio(1); } while (0)
; template <bool F32>
; __device__ __forceinline__ void attn_unit(const AUnit& U, LAS unsigned char* lds, float lam, const float* subg) {
;     ...
;     const int mnt = active ? my_nt : 0;
;     ATT_BASEPRIO_EARLY();
;     bf16x8 pa[4];
; #pragma unroll
;     for (int k = 0; k < 4; ++k) pa[k] = (bf16x8){0, 0, 0, 0, 0, 0, 0, 0};
;     f32x16 p0, p1;
.Lc0_steady:
	s_add_i32 m0, s8, s22
	v_lshl_add_u64 v[4:5], s[6:7], 0, v[146:147]
	v_lshl_add_u64 v[2:3], s[6:7], 0, v[148:149]
	global_load_lds_dwordx4 v[4:5], off
	s_addk_i32 m0, 0x400
	s_add_u32 s26, s6, 0x1fe0000
	global_load_lds_dwordx4 v[2:3], off
	s_addc_u32 s27, s7, 0
	v_lshl_add_u64 v[2:3], s[26:27], 0, v[152:153]
	v_lshl_add_u64 v[4:5], s[26:27], 0, v[150:151]
	s_add_i32 m0, s28, s30
	s_nop 0
	global_load_lds_dwordx4 v[4:5], off
	s_addk_i32 m0, 0x400
	s_nop 0
	global_load_lds_dwordx4 v[2:3], off
	v_add_u32_e32 v0, s22, v191
	v_add_u32_e32 v14, s22, v192
	v_add_u32_e32 v15, s22, v193
	v_add_u32_e32 v171, s22, v194
	v_add_u32_e32 v180, s22, v195
	v_add_u32_e32 v181, s22, v196
	v_add_u32_e32 v253, s22, v197
	v_add_u32_e32 v254, s22, v187
	v_add_u32_e32 v249, s29, v145
	v_add_u32_e32 v250, s29, v159
	v_add_u32_e32 v251, s29, v160
	v_add_u32_e32 v252, s29, v161
	ds_read_b64_tr_b16 v[2:3], v0 offset:49152
	ds_read_b64_tr_b16 v[4:5], v14 offset:49152
	ds_read_b64_tr_b16 v[6:7], v15 offset:49152
	ds_read_b64_tr_b16 v[8:9], v171 offset:49152
	ds_read_b64_tr_b16 v[10:11], v180 offset:49152
	ds_read_b64_tr_b16 v[12:13], v181 offset:49152
	ds_read_b64_tr_b16 v[172:173], v253 offset:49152
	ds_read_b64_tr_b16 v[174:175], v254 offset:49152
	ds_read_b64_tr_b16 v[198:199], v0 offset:53248
	ds_read_b64_tr_b16 v[200:201], v14 offset:53248
	ds_read_b64_tr_b16 v[202:203], v15 offset:53248
	ds_read_b64_tr_b16 v[204:205], v171 offset:53248
	ds_read_b64_tr_b16 v[206:207], v180 offset:53248
	ds_read_b64_tr_b16 v[208:209], v181 offset:53248
	s_setprio 2
	s_waitcnt lgkmcnt(12)
	v_mfma_f32_32x32x16_bf16 v[64:79], v[2:5], v[128:131], v[64:79]
	ds_read_b64_tr_b16 v[176:177], v253 offset:53248
	ds_read_b64_tr_b16 v[178:179], v254 offset:53248
	s_waitcnt lgkmcnt(12)
	v_mfma_f32_32x32x16_bf16 v[48:63], v[6:9], v[128:131], v[48:63]
	ds_read_b64_tr_b16 v[2:3], v0 offset:57344
	ds_read_b64_tr_b16 v[4:5], v14 offset:57344
	s_waitcnt lgkmcnt(12)
	v_mfma_f32_32x32x16_bf16 v[32:47], v[10:13], v[128:131], v[32:47]
	ds_read_b64_tr_b16 v[6:7], v15 offset:57344
	ds_read_b64_tr_b16 v[8:9], v171 offset:57344
	s_waitcnt lgkmcnt(12)
	v_mfma_f32_32x32x16_bf16 v[16:31], v[172:175], v[128:131], v[16:31]
	ds_read_b64_tr_b16 v[10:11], v180 offset:57344
	ds_read_b64_tr_b16 v[12:13], v181 offset:57344
	s_waitcnt lgkmcnt(12)
	v_mfma_f32_32x32x16_bf16 v[64:79], v[198:201], v[132:135], v[64:79]
	ds_read_b64_tr_b16 v[172:173], v253 offset:57344
	ds_read_b64_tr_b16 v[174:175], v254 offset:57344
	s_waitcnt lgkmcnt(12)
	v_mfma_f32_32x32x16_bf16 v[48:63], v[202:205], v[132:135], v[48:63]
	ds_read_b64_tr_b16 v[198:199], v0 offset:61440
	ds_read_b64_tr_b16 v[200:201], v14 offset:61440
	s_waitcnt lgkmcnt(12)
	v_mfma_f32_32x32x16_bf16 v[32:47], v[206:209], v[132:135], v[32:47]
	ds_read_b64_tr_b16 v[202:203], v15 offset:61440
	ds_read_b64_tr_b16 v[204:205], v171 offset:61440
	s_waitcnt lgkmcnt(12)
	v_mfma_f32_32x32x16_bf16 v[16:31], v[176:179], v[132:135], v[16:31]
	ds_read_b64_tr_b16 v[206:207], v180 offset:61440
	ds_read_b64_tr_b16 v[208:209], v181 offset:61440
	s_waitcnt lgkmcnt(12)
	v_mfma_f32_32x32x16_bf16 v[64:79], v[2:5], v[136:139], v[64:79]
	ds_read_b64_tr_b16 v[176:177], v253 offset:61440
	ds_read_b64_tr_b16 v[178:179], v254 offset:61440
	s_waitcnt lgkmcnt(12)
	v_mfma_f32_32x32x16_bf16 v[48:63], v[6:9], v[136:139], v[48:63]
	ds_read_b128 v[2:5], v249
	s_waitcnt lgkmcnt(11)
	v_mfma_f32_32x32x16_bf16 v[32:47], v[10:13], v[136:139], v[32:47]
	ds_read_b128 v[6:9], v249 offset:8192
	s_waitcnt lgkmcnt(10)
	v_mfma_f32_32x32x16_bf16 v[16:31], v[172:175], v[136:139], v[16:31]
	ds_read_b128 v[10:13], v250
	s_waitcnt lgkmcnt(9)
; #define ATT_BAR() do { asm volatile("s_waitcnt lgkmcnt(0)" ::: "memory"); __builtin_amdgcn_s_barrier(); asm volatile("" ::: "memory"); } while (0)
; #define ATT_EVEN(j_, k2_, v1_) do { if (!F32) { if ((j_) + 2 < nt) ATT_DMAK((j_) + 2, k2_); if ((j_) + 1 < nt) ATT_DMAV((j_) + 1, v1_); } } while (0)
; template <bool F32>
; __device__ __forceinline__ void attn_unit(const AUnit& U, LAS unsigned char* lds, float lam, const float* subg) {
;     ...
;         for (int it = 0; it <= nt; ++it) {
;             ATT_EVEN(it, r0, r2);
;             ATT_MM((it >= 1 && it <= mnt), (it < mnt), r0, r1);
;             if (it < mnt) ATT_SM(it);
;             ATT_ODD(it, r2, r1);
;             ATT_BAR();
;             { const int t_ = r0; r0 = r1; r1 = r2; r2 = t_; }
	v_mfma_f32_32x32x16_bf16 v[64:79], v[198:201], v[140:143], v[64:79]
	ds_read_b128 v[172:175], v250 offset:8192
	s_waitcnt lgkmcnt(8)
	v_mfma_f32_32x32x16_bf16 v[48:63], v[202:205], v[140:143], v[48:63]
	ds_read_b128 v[198:201], v251
	s_waitcnt lgkmcnt(7)
	v_mfma_f32_32x32x16_bf16 v[32:47], v[206:209], v[140:143], v[32:47]
	ds_read_b128 v[202:205], v251 offset:8192
	s_waitcnt lgkmcnt(6)
	v_mfma_f32_32x32x16_bf16 v[16:31], v[176:179], v[140:143], v[16:31]
	ds_read_b128 v[206:209], v252
	ds_read_b128 v[176:179], v252 offset:8192
	s_waitcnt lgkmcnt(7)
	v_mfma_f32_32x32x16_bf16 v[80:95], v[2:5], v[112:115], 0
	s_waitcnt lgkmcnt(6)
	v_mfma_f32_32x32x16_bf16 v[96:111], v[6:9], v[112:115], 0
	s_waitcnt lgkmcnt(5)
	v_mfma_f32_32x32x16_bf16 v[80:95], v[10:13], v[116:119], v[80:95]
	s_waitcnt lgkmcnt(4)
	v_mfma_f32_32x32x16_bf16 v[96:111], v[172:175], v[116:119], v[96:111]
	s_waitcnt lgkmcnt(3)
	v_mfma_f32_32x32x16_bf16 v[80:95], v[198:201], v[120:123], v[80:95]
	s_waitcnt lgkmcnt(2)
	v_mfma_f32_32x32x16_bf16 v[96:111], v[202:205], v[120:123], v[96:111]
	s_waitcnt lgkmcnt(1)
	v_mfma_f32_32x32x16_bf16 v[80:95], v[206:209], v[124:127], v[80:95]
	s_waitcnt lgkmcnt(0)
	v_mfma_f32_32x32x16_bf16 v[96:111], v[176:179], v[124:127], v[96:111]
	s_setprio 0
	s_add_u32 s6, s6, 0x20000
	s_addc_u32 s7, s7, 0
	s_mov_b32 s92, s22
	s_mov_b32 s22, s29
	s_mov_b32 s29, s30
	s_mov_b32 s30, s92
	s_add_i32 s31, s31, 1
	s_nop 1
	v_exp_f32_e32 v80, v80
	v_exp_f32_e32 v81, v81
	v_exp_f32_e32 v82, v82
	v_exp_f32_e32 v83, v83
	v_exp_f32_e32 v84, v84
	v_exp_f32_e32 v85, v85
	v_exp_f32_e32 v86, v86
	v_exp_f32_e32 v87, v87
	v_add_f32_e32 v2, v80, v84
	v_add_f32_e32 v3, v81, v85
	v_add_f32_e32 v4, v82, v86
	v_add_f32_e32 v5, v83, v87
	v_cvt_pk_bf16_f32 v128, v80, v81
	v_cvt_pk_bf16_f32 v129, v82, v83
	v_exp_f32_e32 v88, v88
	v_exp_f32_e32 v89, v89
	v_exp_f32_e32 v90, v90
	v_exp_f32_e32 v91, v91
	v_cvt_pk_bf16_f32 v130, v84, v85
	v_cvt_pk_bf16_f32 v131, v86, v87
	v_add_f32_e32 v2, v2, v88
	v_add_f32_e32 v3, v3, v89
	v_add_f32_e32 v4, v4, v90
	v_add_f32_e32 v5, v5, v91
	v_exp_f32_e32 v92, v92
	v_exp_f32_e32 v93, v93
	v_exp_f32_e32 v94, v94
	v_exp_f32_e32 v95, v95
	v_cvt_pk_bf16_f32 v132, v88, v89
	v_cvt_pk_bf16_f32 v133, v90, v91
	v_add_f32_e32 v2, v2, v92
	v_add_f32_e32 v3, v3, v93
	v_add_f32_e32 v4, v4, v94
	v_add_f32_e32 v5, v5, v95
	v_exp_f32_e32 v96, v96
	v_exp_f32_e32 v97, v97
	v_exp_f32_e32 v98, v98
	v_exp_f32_e32 v99, v99
	v_cvt_pk_bf16_f32 v134, v92, v93
	v_cvt_pk_bf16_f32 v135, v94, v95
	v_add_f32_e32 v2, v2, v96
	v_add_f32_e32 v3, v3, v97
	v_add_f32_e32 v4, v4, v98
	v_add_f32_e32 v5, v5, v99
	v_exp_f32_e32 v100, v100
	v_exp_f32_e32 v101, v101
	v_exp_f32_e32 v102, v102
	v_exp_f32_e32 v103, v103
	v_cvt_pk_bf16_f32 v136, v96, v97
	v_cvt_pk_bf16_f32 v137, v98, v99
	v_add_f32_e32 v2, v2, v100
	v_add_f32_e32 v3, v3, v101
	v_add_f32_e32 v4, v4, v102
	v_add_f32_e32 v5, v5, v103
	v_exp_f32_e32 v104, v104
	v_exp_f32_e32 v105, v105
	v_exp_f32_e32 v106, v106
	v_exp_f32_e32 v107, v107
	v_cvt_pk_bf16_f32 v138, v100, v101
	v_cvt_pk_bf16_f32 v139, v102, v103
	v_add_f32_e32 v2, v2, v104
	v_add_f32_e32 v3, v3, v105
	v_add_f32_e32 v4, v4, v106
	v_add_f32_e32 v5, v5, v107
	v_exp_f32_e32 v108, v108
	v_exp_f32_e32 v109, v109
	v_exp_f32_e32 v110, v110
	v_exp_f32_e32 v111, v111
	v_cvt_pk_bf16_f32 v140, v104, v105
	v_cvt_pk_bf16_f32 v141, v106, v107
	v_add_f32_e32 v2, v2, v108
	v_add_f32_e32 v3, v3, v109
	v_add_f32_e32 v4, v4, v110
	v_add_f32_e32 v5, v5, v111
	v_add_f32_e32 v2, v2, v3
	v_add_f32_e32 v4, v4, v5
	v_cvt_pk_bf16_f32 v142, v108, v109
	v_add_f32_e32 v2, v2, v4
	v_cvt_pk_bf16_f32 v143, v110, v111
	v_add_f32_e32 v165, v165, v2
	s_waitcnt vmcnt(4)
	s_waitcnt lgkmcnt(0)
	s_barrier
	s_cmp_lt_i32 s31, s94
	s_cbranch_scc1 .Lc0_steady
	s_branch .LBB0_735
